# grid barrier: non-leader WGs poll TOPGEN directly instead of per-XCD XGEN (one hop fewer); leader XGEN atomic removed
# speedup vs baseline: 1.0066x; 1.0066x over previous
.LBB0_319:
	s_or_b64 exec, exec, s[2:3]
	v_cvt_f32_u32_e32 v4, v2
	s_waitcnt vmcnt(0)
	v_readfirstlane_b32 s2, v3
	v_sub_u32_e32 v3, 0, v2
	v_rcp_iflag_f32_e32 v4, v4
	v_add_u32_e32 v5, s2, v1
	v_mul_f32_e32 v4, 0x4f7ffffe, v4
	v_cvt_u32_f32_e32 v4, v4
	v_mul_lo_u32 v1, v3, v4
	v_mul_hi_u32 v1, v4, v1
	v_add_u32_e32 v1, v4, v1
	v_mul_hi_u32 v1, v5, v1
	v_mul_lo_u32 v3, v1, v2
	v_sub_u32_e32 v3, v5, v3
	v_add_u32_e32 v4, 1, v1
	v_cmp_ge_u32_e32 vcc, v3, v2
	s_nop 1
	v_cndmask_b32_e32 v1, v1, v4, vcc
	v_sub_u32_e32 v4, v3, v2
	v_cndmask_b32_e32 v3, v3, v4, vcc
	v_add_u32_e32 v4, 1, v1
	v_cmp_ge_u32_e32 vcc, v3, v2
	v_add_u32_e32 v3, 1, v5
	s_nop 0
	v_cndmask_b32_e32 v1, v1, v4, vcc
	v_mul_lo_u32 v4, v2, v1
	v_add_u32_e32 v2, v4, v2
	v_cmp_ne_u32_e32 vcc, v3, v2
	s_and_saveexec_b64 s[2:3], vcc
	s_xor_b64 s[2:3], exec, s[2:3]
	s_cbranch_execz .LBB0_333
	v_readlane_b32 s8, v255, 14
	v_readlane_b32 s9, v255, 15
	s_waitcnt lgkmcnt(0)
	s_nop 3
	global_load_dword v0, v193, s[8:9] sc1
	s_waitcnt vmcnt(0)
	v_cmp_eq_u32_e32 vcc, v0, v1
	s_and_saveexec_b64 s[12:13], vcc
	s_cbranch_execz .LBB0_332
	s_mov_b32 s10, 1
	s_mov_b64 s[36:37], 0
	s_branch .LBB0_323

.LBB0_325:
	v_readlane_b32 s8, v255, 14
	v_readlane_b32 s9, v255, 15
	s_add_i32 s10, s10, 1
	s_mov_b64 s[44:45], -1
	s_nop 2
	global_load_dword v0, v193, s[8:9] sc1
	s_waitcnt vmcnt(0)
	v_cmp_ne_u32_e32 vcc, v0, v1
	s_orn2_b64 s[40:41], vcc, exec
	s_branch .LBB0_322

.LBB0_350:
	s_or_b64 exec, exec, s[2:3]
	s_mov_b64 s[2:3], exec
	v_mbcnt_lo_u32_b32 v0, s2, 0
	v_mbcnt_hi_u32_b32 v0, s3, v0
	v_cmp_eq_u32_e32 vcc, 0, v0
	s_waitcnt vmcnt(0)
	buffer_inv sc1
	s_and_saveexec_b64 s[12:13], vcc
	s_cbranch_execz .LBB0_352
	s_bcnt1_i32_b64 s2, s[2:3]
	v_mov_b32_e32 v0, s2
	v_readlane_b32 s2, v255, 10
	v_readlane_b32 s3, v255, 11
	s_nop 4
.LBB0_352:
	s_or_b64 exec, exec, s[12:13]
	s_waitcnt vmcnt(0)

.LBB0_510:
	s_or_b64 exec, exec, s[2:3]
	s_mov_b64 s[2:3], exec
	v_mbcnt_lo_u32_b32 v0, s2, 0
	v_mbcnt_hi_u32_b32 v0, s3, v0
	v_cmp_eq_u32_e32 vcc, 0, v0
	s_waitcnt vmcnt(0)
	buffer_inv sc1
	s_and_saveexec_b64 s[12:13], vcc
	s_cbranch_execz .LBB0_512
	s_bcnt1_i32_b64 s2, s[2:3]
	v_mov_b32_e32 v0, s2
	v_readlane_b32 s2, v255, 10
	v_readlane_b32 s3, v255, 11
	s_nop 4
.LBB0_512:
	s_or_b64 exec, exec, s[12:13]
	s_waitcnt vmcnt(0)

.LBB0_594:
	s_or_b64 exec, exec, s[2:3]
	s_mov_b64 s[2:3], exec
	v_mbcnt_lo_u32_b32 v0, s2, 0
	v_mbcnt_hi_u32_b32 v0, s3, v0
	v_cmp_eq_u32_e32 vcc, 0, v0
	s_waitcnt vmcnt(0)
	buffer_inv sc1
	s_and_saveexec_b64 s[12:13], vcc
	s_cbranch_execz .LBB0_596
	s_bcnt1_i32_b64 s2, s[2:3]
	v_mov_b32_e32 v0, s2
	v_readlane_b32 s2, v255, 10
	v_readlane_b32 s3, v255, 11
	s_nop 4
.LBB0_596:
	s_or_b64 exec, exec, s[12:13]
	s_waitcnt vmcnt(0)

.LBB0_695:
	s_or_b64 exec, exec, s[2:3]
	s_mov_b64 s[2:3], exec
	v_mbcnt_lo_u32_b32 v0, s2, 0
	v_mbcnt_hi_u32_b32 v0, s3, v0
	v_cmp_eq_u32_e32 vcc, 0, v0
	s_waitcnt vmcnt(0)
	buffer_inv sc1
	s_and_saveexec_b64 s[12:13], vcc
	s_cbranch_execz .LBB0_697
	s_bcnt1_i32_b64 s2, s[2:3]
	v_mov_b32_e32 v0, s2
	v_readlane_b32 s2, v255, 10
	v_readlane_b32 s3, v255, 11
	s_nop 4
.LBB0_697:
	s_or_b64 exec, exec, s[12:13]
	s_waitcnt vmcnt(0)

.LBB0_758:
	s_or_b64 exec, exec, s[2:3]
	s_mov_b64 s[2:3], exec
	v_mbcnt_lo_u32_b32 v0, s2, 0
	v_mbcnt_hi_u32_b32 v0, s3, v0
	v_cmp_eq_u32_e32 vcc, 0, v0
	s_waitcnt vmcnt(0)
	buffer_inv sc1
	s_and_saveexec_b64 s[12:13], vcc
	s_cbranch_execz .LBB0_760
	s_bcnt1_i32_b64 s2, s[2:3]
	v_mov_b32_e32 v0, s2
	v_readlane_b32 s2, v255, 10
	v_readlane_b32 s3, v255, 11
	s_nop 4
.LBB0_760:
	s_or_b64 exec, exec, s[12:13]
	s_waitcnt vmcnt(0)

.LBB0_821:
	s_or_b64 exec, exec, s[2:3]
	s_mov_b64 s[2:3], exec
	v_mbcnt_lo_u32_b32 v0, s2, 0
	v_mbcnt_hi_u32_b32 v0, s3, v0
	v_cmp_eq_u32_e32 vcc, 0, v0
	s_waitcnt vmcnt(0)
	buffer_inv sc1
	s_and_saveexec_b64 s[12:13], vcc
	s_cbranch_execz .LBB0_823
	s_bcnt1_i32_b64 s2, s[2:3]
	v_mov_b32_e32 v0, s2
	v_readlane_b32 s2, v255, 10
	v_readlane_b32 s3, v255, 11
	s_nop 4
.LBB0_823:
	s_or_b64 exec, exec, s[12:13]
	s_waitcnt vmcnt(0)

.LBB0_976:
	s_or_b64 exec, exec, s[2:3]
	v_cvt_f32_u32_e32 v4, v2
	s_waitcnt vmcnt(0)
	v_readfirstlane_b32 s2, v3
	v_sub_u32_e32 v3, 0, v2
	v_rcp_iflag_f32_e32 v4, v4
	v_add_u32_e32 v5, s2, v1
	v_mul_f32_e32 v4, 0x4f7ffffe, v4
	v_cvt_u32_f32_e32 v4, v4
	v_mul_lo_u32 v1, v3, v4
	v_mul_hi_u32 v1, v4, v1
	v_add_u32_e32 v1, v4, v1
	v_mul_hi_u32 v1, v5, v1
	v_mul_lo_u32 v3, v1, v2
	v_sub_u32_e32 v3, v5, v3
	v_add_u32_e32 v4, 1, v1
	v_cmp_ge_u32_e32 vcc, v3, v2
	s_nop 1
	v_cndmask_b32_e32 v1, v1, v4, vcc
	v_sub_u32_e32 v4, v3, v2
	v_cndmask_b32_e32 v3, v3, v4, vcc
	v_add_u32_e32 v4, 1, v1
	v_cmp_ge_u32_e32 vcc, v3, v2
	v_add_u32_e32 v3, 1, v5
	s_nop 0
	v_cndmask_b32_e32 v1, v1, v4, vcc
	v_mul_lo_u32 v4, v2, v1
	v_add_u32_e32 v2, v4, v2
	v_cmp_ne_u32_e32 vcc, v3, v2
	s_and_saveexec_b64 s[2:3], vcc
	s_xor_b64 s[2:3], exec, s[2:3]
	s_cbranch_execz .LBB0_990
	v_readlane_b32 s8, v255, 14
	v_readlane_b32 s9, v255, 15
	s_waitcnt lgkmcnt(0)
	s_nop 3
	global_load_dword v0, v193, s[8:9] sc1
	s_waitcnt vmcnt(0)
	v_cmp_eq_u32_e32 vcc, v0, v1
	s_and_saveexec_b64 s[12:13], vcc
	s_cbranch_execz .LBB0_989
	s_mov_b32 s10, 1
	s_mov_b64 s[38:39], 0
	s_branch .LBB0_980

.LBB0_982:
	v_readlane_b32 s8, v255, 14
	v_readlane_b32 s9, v255, 15
	s_add_i32 s10, s10, 1
	s_mov_b64 s[46:47], -1
	s_nop 2
	global_load_dword v0, v193, s[8:9] sc1
	s_waitcnt vmcnt(0)
	v_cmp_ne_u32_e32 vcc, v0, v1
	s_orn2_b64 s[44:45], vcc, exec
	s_branch .LBB0_979

.LBB0_1007:
	s_or_b64 exec, exec, s[2:3]
	s_mov_b64 s[2:3], exec
	v_mbcnt_lo_u32_b32 v0, s2, 0
	v_mbcnt_hi_u32_b32 v0, s3, v0
	v_cmp_eq_u32_e32 vcc, 0, v0
	s_waitcnt vmcnt(0)
	buffer_inv sc1
	s_and_saveexec_b64 s[12:13], vcc
	s_cbranch_execz .LBB0_1009
	s_bcnt1_i32_b64 s2, s[2:3]
	v_mov_b32_e32 v0, s2
	v_readlane_b32 s2, v255, 10
	v_readlane_b32 s3, v255, 11
	s_nop 4
.LBB0_1009:
	s_or_b64 exec, exec, s[12:13]
	s_waitcnt vmcnt(0)

.LBB0_1285:
	s_or_b64 exec, exec, s[2:3]
	s_mov_b64 s[2:3], exec
	v_mbcnt_lo_u32_b32 v0, s2, 0
	v_mbcnt_hi_u32_b32 v0, s3, v0
	v_cmp_eq_u32_e32 vcc, 0, v0
	s_waitcnt vmcnt(0)
	buffer_inv sc1
	s_and_saveexec_b64 s[12:13], vcc
	s_cbranch_execz .LBB0_289
	s_bcnt1_i32_b64 s2, s[2:3]
	v_mov_b32_e32 v0, s2
	v_readlane_b32 s2, v255, 10
	v_readlane_b32 s3, v255, 11
	s_nop 4
	s_branch .LBB0_289
